# adaLN for layers 1-3 deferred from the prologue to the CUs idle during the two GLA scans (prologue keeps layer 0's 64 units); hook re-enters the prologue adaLN code
# baseline (speedup 1.0000x reference)
; #define LAS __attribute__((address_space(3)))
; DI unsigned char* launder_ptr(unsigned char* p) { asm volatile("; launder ptr" : "+s"(p)); return p; }
; DI Frame launder(const Frame& F0) { Frame F = F0; asm volatile("; launder frame" : "+v"(F.tid), "+v"(F.lane), "+s"(F.wave), "+s"(F.vcu)); return F; }
; DI void phase_prologue(const Frame& F0, const Args& a) {
;     const Frame F = launder(F0);
;     unsigned char* ws = launder_ptr(a.ws);
;     {
;         LAS float* sv = (LAS float*)(F.lds);
;         LAS float* red = (LAS float*)(F.lds + 24576);
;         for (int i = F.tid; i < 3 * DM; i += 512) { const int mb = i / DM, k = i % DM; const float cv = mb < 2 ? a.c[mb * DM + k] : a.c_ctx[k]; sv[i] = cv / (1.0f + __expf(-cv)); }
;         __syncthreads();
;         float* mod = (float*)(ws + WS_MOD);
;         for (int unit = F.vcu; unit < DEPTH * 64; unit += F.G) {
; template <unsigned SITE_MASK> __global__ void __launch_bounds__(NWAVES * 64, 2) fwd_kernel(Args args) {
;     extern __shared__ __attribute__((aligned(16))) unsigned char lds_raw[];
;     Frame F; F.lds = (LAS unsigned char*)lds_raw;
;     F.tid = threadIdx.x; F.lane = F.tid & 63; F.wave = __builtin_amdgcn_readfirstlane(F.tid >> 6);
;     F.G = gridDim.x; { const int bx = blockIdx.x; F.vcu = (F.G % 8 == 0) ? (bx % 8) * (F.G / 8) + bx / 8 : bx; }
;     unsigned char* ws = args.ws;
;     volatile LAS unsigned* MISC = (volatile LAS unsigned*)(F.lds + MISC_OFF);
;     for (int u = F.tid; u < (LDS_BYTES - MISC_OFF) / 4; u += NWAVES * 64) ((LAS unsigned*)(F.lds + MISC_OFF))[u] = 0u;
;     __syncthreads();
;     const int lo = args.ph_lo, hi = args.ph_hi;
;     XcdBarrier bar; bar.bar = (unsigned*)(ws + WS_CTL) + CW_BAR; bar.x = 0; bar.st = nullptr;
;     if (hi - lo > 1) bar = xcd_barrier_post((unsigned*)(ws + WS_CTL) + CW_BAR, MISC + 8);
.LBB0_8:
	v_writelane_b32 v252, s12, 7
	s_load_dwordx16 s[12:27], s[0:1], 0x0
	s_lshr_b32 s50, s8, 6
	s_cmp_lt_i32 s52, 1
	v_and_b32_e32 v222, 63, v0
	s_waitcnt lgkmcnt(0)
	v_writelane_b32 v252, s12, 8
	s_nop 1
	v_writelane_b32 v252, s13, 9
	v_writelane_b32 v252, s14, 10
	v_writelane_b32 v252, s15, 11
	v_writelane_b32 v252, s16, 12
	v_writelane_b32 v252, s17, 13
	v_writelane_b32 v252, s18, 14
	v_writelane_b32 v252, s19, 15
	v_writelane_b32 v252, s20, 16
	v_writelane_b32 v252, s21, 17
	v_writelane_b32 v252, s22, 18
	v_writelane_b32 v252, s23, 19
	v_writelane_b32 v252, s24, 20
	v_writelane_b32 v252, s25, 21
	v_writelane_b32 v252, s26, 22
	v_writelane_b32 v252, s27, 23
	s_load_dwordx16 s[12:27], s[0:1], 0x40
	s_cselect_b64 s[0:1], -1, 0
	s_cmp_gt_i32 s52, 0
	s_waitcnt lgkmcnt(0)
	v_writelane_b32 v252, s12, 24
	s_nop 1
	v_writelane_b32 v252, s13, 25
	v_writelane_b32 v252, s14, 26
	v_writelane_b32 v252, s15, 27
	v_writelane_b32 v252, s16, 28
	v_writelane_b32 v252, s17, 29
	v_writelane_b32 v252, s18, 30
	v_writelane_b32 v252, s19, 31
	v_writelane_b32 v252, s20, 32
	v_writelane_b32 v252, s21, 33
	v_writelane_b32 v252, s22, 34
	v_writelane_b32 v252, s23, 35
	v_writelane_b32 v252, s24, 36
	v_writelane_b32 v252, s25, 37
	v_writelane_b32 v252, s26, 38
	v_writelane_b32 v252, s27, 39
	v_writelane_b32 v252, s0, 40
	s_nop 1
	v_writelane_b32 v252, s1, 41
	s_cselect_b64 s[0:1], -1, 0
	s_cmp_lt_i32 s53, 1
	s_cselect_b64 s[4:5], -1, 0
	s_or_b64 s[0:1], s[0:1], s[4:5]
	s_mov_b64 s[4:5], s[52:53]
	s_mov_b32 s6, s54
	v_writelane_b32 v252, s4, 42
	s_and_b64 vcc, exec, s[0:1]
	s_nop 0
	v_writelane_b32 v252, s5, 43
	v_writelane_b32 v252, s6, 44
	v_writelane_b32 v252, s7, 45
	v_writelane_b32 v252, s30, 46
	s_nop 1
	v_writelane_b32 v252, s31, 47
	v_writelane_b32 v252, s51, 48
	v_writelane_b32 v252, s50, 49
	s_cbranch_vccnz .LBB0_99
	s_lshl_b32 s71, s3, 9
	v_cvt_f32_u32_e32 v1, s71
	v_writelane_b32 v252, s72, 50
	s_and_b32 s0, s54, 1
	s_lshl_b32 s85, s3, 11
	v_rcp_iflag_f32_e32 v1, v1
	v_writelane_b32 v252, s73, 51
	v_writelane_b32 v252, s0, 52
	s_lshl_b32 s0, s3, 3
	v_mul_f32_e32 v1, 0x4f7ffffe, v1
	v_cvt_u32_f32_e32 v1, v1
	v_writelane_b32 v252, s0, 53
	s_sub_i32 s0, 0, s71
	s_ashr_i32 s1, s71, 31
	v_mul_lo_u32 v2, s0, v1
	v_mul_hi_u32 v2, v1, v2
	s_mov_b32 s0, s71
	s_lshl_b32 s77, s3, 10
	s_mov_b32 s65, 0
	s_mov_b32 s35, s85
	s_mov_b32 s37, s85
	s_mov_b32 s39, s85
	v_add_u32_e32 v72, v1, v2
	v_mov_b32_e32 v55, 0
	s_lshl_b64 s[66:67], s[0:1], 1
	s_lshl_b32 s24, s3, 16
	v_mov_b32_e32 v73, 0xff
	s_mov_b32 s43, 0xc000
	s_add_i32 s79, 0, 0x6000
	s_mov_b32 s75, 0x40000
	s_mov_b32 s69, 0x7f800000
	s_mov_b32 s72, 0x3e75aa41
	s_mov_b32 s74, 0x40234736
	s_mov_b32 s76, 0xc0a55e0e
	s_mov_b32 s78, 0x40490fdb
	s_mov_b32 s36, 0x3d4be544
	s_mov_b32 s38, 0xbfaad1da
	s_brev_b32 s33, 1
	s_mov_b32 s41, 0x20000
	s_movk_i32 s84, 0x7fff
	v_mov_b32_e32 v74, 0xbf1f24be
	v_mov_b32_e32 v75, 0x3e642e9d
	s_movk_i32 s70, 0x101
	s_movk_i32 s34, 0xfe00
	s_movk_i32 s73, 0x6080
	v_mov_b32_e32 v76, 0x7fc00000
	v_mov_b32_e32 v77, 0xffc00000
	s_mov_b32 s98, 0
	s_mov_b32 s88, 0
	s_mov_b32 s40, 0x4081e0d3
	s_mov_b32 s42, 0xc09de9e6
	s_mov_b32 s68, 0x39800000
	s_branch .LBB0_12

; DI void phase_prologue(const Frame& F0, const Args& a) {
;     ...
;         for (int i = F.tid; i < 3 * DM; i += 512) { const int mb = i / DM, k = i % DM; const float cv = mb < 2 ? a.c[mb * DM + k] : a.c_ctx[k]; sv[i] = cv / (1.0f + __expf(-cv)); }
;         __syncthreads();
.LBB0_12:
	v_mov_b32_e32 v1, v0
	s_mov_b32 s44, s50
	v_mov_b32_e32 v78, v222
	v_readlane_b32 s60, v252, 48
	s_cmp_lg_u32 s98, 0
	s_cselect_b32 s60, s99, s60
	v_readlane_b32 s86, v252, 46
	s_movk_i32 s0, 0x1800
	v_readlane_b32 s87, v252, 47
	v_cmp_gt_i32_e32 vcc, s0, v1
	s_and_saveexec_b64 s[0:1], vcc
	s_cbranch_execz .LBB0_19
	v_readlane_b32 s10, v252, 10
	v_readlane_b32 s11, v252, 11
	v_readlane_b32 s20, v252, 14
	v_readlane_b32 s21, v252, 15
	v_lshlrev_b32_e32 v4, 2, v1
	v_add_u32_e32 v11, 0x1000, v4
	v_add_u32_e32 v12, 0x2000, v4
	v_add_u32_e32 v13, 0x3000, v4
	v_and_b32_e32 v14, 7, v1
	v_lshrrev_b32_e32 v15, 3, v1
	v_lshlrev_b32_e32 v14, 10, v14
	v_lshl_add_u32 v14, v15, 2, v14
	global_load_dword v20, v4, s[10:11]
	global_load_dword v21, v4, s[10:11] offset:2048
	global_load_dword v22, v11, s[10:11]
	global_load_dword v23, v11, s[10:11] offset:2048
	global_load_dword v24, v12, s[10:11]
	global_load_dword v25, v12, s[10:11] offset:2048
	global_load_dword v26, v13, s[10:11]
	global_load_dword v27, v13, s[10:11] offset:2048
	global_load_dword v28, v4, s[20:21]
	global_load_dword v29, v4, s[20:21] offset:2048
	global_load_dword v30, v11, s[20:21]
	global_load_dword v31, v11, s[20:21] offset:2048
	s_waitcnt vmcnt(11)
	v_mov_b32_e32 v2, v20
	v_mul_f32_e32 v3, 0xbfb8aa3b, v2
	v_exp_f32_e32 v3, v3
	s_nop 0
	v_add_f32_e32 v3, 1.0, v3
	v_div_scale_f32 v5, s[6:7], v3, v3, v2
	v_rcp_f32_e32 v7, v5
	v_div_scale_f32 v8, vcc, v2, v3, v2
	v_fma_f32 v9, -v5, v7, 1.0
	v_fmac_f32_e32 v7, v9, v7
	v_mul_f32_e32 v9, v8, v7
	v_fma_f32 v10, -v5, v9, v8
	v_fmac_f32_e32 v9, v10, v7
	v_fma_f32 v5, -v5, v9, v8
	v_div_fmas_f32 v5, v5, v7, v9
	v_div_fixup_f32 v2, v5, v3, v2
	ds_write_b32 v14, v2
	s_waitcnt vmcnt(10)
	v_mov_b32_e32 v2, v21
	v_mul_f32_e32 v3, 0xbfb8aa3b, v2
	v_exp_f32_e32 v3, v3
	s_nop 0
	v_add_f32_e32 v3, 1.0, v3
	v_div_scale_f32 v5, s[6:7], v3, v3, v2
	v_rcp_f32_e32 v7, v5
	v_div_scale_f32 v8, vcc, v2, v3, v2
	v_fma_f32 v9, -v5, v7, 1.0
	v_fmac_f32_e32 v7, v9, v7
	v_mul_f32_e32 v9, v8, v7
	v_fma_f32 v10, -v5, v9, v8
	v_fmac_f32_e32 v9, v10, v7
	v_fma_f32 v5, -v5, v9, v8
	v_div_fmas_f32 v5, v5, v7, v9
	v_div_fixup_f32 v2, v5, v3, v2
	ds_write_b32 v14, v2 offset:256
	s_waitcnt vmcnt(9)
	v_mov_b32_e32 v2, v22
	v_mul_f32_e32 v3, 0xbfb8aa3b, v2
	v_exp_f32_e32 v3, v3
	s_nop 0
	v_add_f32_e32 v3, 1.0, v3
	v_div_scale_f32 v5, s[6:7], v3, v3, v2
	v_rcp_f32_e32 v7, v5
	v_div_scale_f32 v8, vcc, v2, v3, v2
	v_fma_f32 v9, -v5, v7, 1.0
	v_fmac_f32_e32 v7, v9, v7
	v_mul_f32_e32 v9, v8, v7
	v_fma_f32 v10, -v5, v9, v8
	v_fmac_f32_e32 v9, v10, v7
	v_fma_f32 v5, -v5, v9, v8
	v_div_fmas_f32 v5, v5, v7, v9
	v_div_fixup_f32 v2, v5, v3, v2
	ds_write_b32 v14, v2 offset:512
	s_waitcnt vmcnt(8)
	v_mov_b32_e32 v2, v23
	v_mul_f32_e32 v3, 0xbfb8aa3b, v2
	v_exp_f32_e32 v3, v3
	s_nop 0
	v_add_f32_e32 v3, 1.0, v3
	v_div_scale_f32 v5, s[6:7], v3, v3, v2
	v_rcp_f32_e32 v7, v5
	v_div_scale_f32 v8, vcc, v2, v3, v2
	v_fma_f32 v9, -v5, v7, 1.0
	v_fmac_f32_e32 v7, v9, v7
	v_mul_f32_e32 v9, v8, v7
	v_fma_f32 v10, -v5, v9, v8
	v_fmac_f32_e32 v9, v10, v7
	v_fma_f32 v5, -v5, v9, v8
	v_div_fmas_f32 v5, v5, v7, v9
	v_div_fixup_f32 v2, v5, v3, v2
	ds_write_b32 v14, v2 offset:768
	s_waitcnt vmcnt(7)
	v_mov_b32_e32 v2, v24
	v_mul_f32_e32 v3, 0xbfb8aa3b, v2
	v_exp_f32_e32 v3, v3
	s_nop 0
	v_add_f32_e32 v3, 1.0, v3
	v_div_scale_f32 v5, s[6:7], v3, v3, v2
	v_rcp_f32_e32 v7, v5
	v_div_scale_f32 v8, vcc, v2, v3, v2
	v_fma_f32 v9, -v5, v7, 1.0
	v_fmac_f32_e32 v7, v9, v7
	v_mul_f32_e32 v9, v8, v7
	v_fma_f32 v10, -v5, v9, v8
	v_fmac_f32_e32 v9, v10, v7
	v_fma_f32 v5, -v5, v9, v8
	v_div_fmas_f32 v5, v5, v7, v9
	v_div_fixup_f32 v2, v5, v3, v2
	ds_write_b32 v14, v2 offset:8192
	s_waitcnt vmcnt(6)
	v_mov_b32_e32 v2, v25
	v_mul_f32_e32 v3, 0xbfb8aa3b, v2
	v_exp_f32_e32 v3, v3
	s_nop 0
	v_add_f32_e32 v3, 1.0, v3
	v_div_scale_f32 v5, s[6:7], v3, v3, v2
	v_rcp_f32_e32 v7, v5
	v_div_scale_f32 v8, vcc, v2, v3, v2
	v_fma_f32 v9, -v5, v7, 1.0
	v_fmac_f32_e32 v7, v9, v7
	v_mul_f32_e32 v9, v8, v7
	v_fma_f32 v10, -v5, v9, v8
	v_fmac_f32_e32 v9, v10, v7
	v_fma_f32 v5, -v5, v9, v8
	v_div_fmas_f32 v5, v5, v7, v9
	v_div_fixup_f32 v2, v5, v3, v2
	ds_write_b32 v14, v2 offset:8448
	s_waitcnt vmcnt(5)
; DI void phase_prologue(const Frame& F0, const Args& a) {
;     ...
;         for (int i = F.tid; i < 3 * DM; i += 512) { const int mb = i / DM, k = i % DM; const float cv = mb < 2 ? a.c[mb * DM + k] : a.c_ctx[k]; sv[i] = cv / (1.0f + __expf(-cv)); }
;         __syncthreads();
;         float* mod = (float*)(ws + WS_MOD);
;         for (int unit = F.vcu; unit < DEPTH * 64; unit += F.G) {
;             const int li = unit >> 6, cb = unit & 63, n0 = cb * 192;
	v_mov_b32_e32 v2, v26
	v_mul_f32_e32 v3, 0xbfb8aa3b, v2
	v_exp_f32_e32 v3, v3
	s_nop 0
	v_add_f32_e32 v3, 1.0, v3
	v_div_scale_f32 v5, s[6:7], v3, v3, v2
	v_rcp_f32_e32 v7, v5
	v_div_scale_f32 v8, vcc, v2, v3, v2
	v_fma_f32 v9, -v5, v7, 1.0
	v_fmac_f32_e32 v7, v9, v7
	v_mul_f32_e32 v9, v8, v7
	v_fma_f32 v10, -v5, v9, v8
	v_fmac_f32_e32 v9, v10, v7
	v_fma_f32 v5, -v5, v9, v8
	v_div_fmas_f32 v5, v5, v7, v9
	v_div_fixup_f32 v2, v5, v3, v2
	ds_write_b32 v14, v2 offset:8704
	s_waitcnt vmcnt(4)
	v_mov_b32_e32 v2, v27
	v_mul_f32_e32 v3, 0xbfb8aa3b, v2
	v_exp_f32_e32 v3, v3
	s_nop 0
	v_add_f32_e32 v3, 1.0, v3
	v_div_scale_f32 v5, s[6:7], v3, v3, v2
	v_rcp_f32_e32 v7, v5
	v_div_scale_f32 v8, vcc, v2, v3, v2
	v_fma_f32 v9, -v5, v7, 1.0
	v_fmac_f32_e32 v7, v9, v7
	v_mul_f32_e32 v9, v8, v7
	v_fma_f32 v10, -v5, v9, v8
	v_fmac_f32_e32 v9, v10, v7
	v_fma_f32 v5, -v5, v9, v8
	v_div_fmas_f32 v5, v5, v7, v9
	v_div_fixup_f32 v2, v5, v3, v2
	ds_write_b32 v14, v2 offset:8960
	s_waitcnt vmcnt(3)
	v_mov_b32_e32 v2, v28
	v_mul_f32_e32 v3, 0xbfb8aa3b, v2
	v_exp_f32_e32 v3, v3
	s_nop 0
	v_add_f32_e32 v3, 1.0, v3
	v_div_scale_f32 v5, s[6:7], v3, v3, v2
	v_rcp_f32_e32 v7, v5
	v_div_scale_f32 v8, vcc, v2, v3, v2
	v_fma_f32 v9, -v5, v7, 1.0
	v_fmac_f32_e32 v7, v9, v7
	v_mul_f32_e32 v9, v8, v7
	v_fma_f32 v10, -v5, v9, v8
	v_fmac_f32_e32 v9, v10, v7
	v_fma_f32 v5, -v5, v9, v8
	v_div_fmas_f32 v5, v5, v7, v9
	v_div_fixup_f32 v2, v5, v3, v2
	ds_write_b32 v14, v2 offset:16384
	s_waitcnt vmcnt(2)
	v_mov_b32_e32 v2, v29
	v_mul_f32_e32 v3, 0xbfb8aa3b, v2
	v_exp_f32_e32 v3, v3
	s_nop 0
	v_add_f32_e32 v3, 1.0, v3
	v_div_scale_f32 v5, s[6:7], v3, v3, v2
	v_rcp_f32_e32 v7, v5
	v_div_scale_f32 v8, vcc, v2, v3, v2
	v_fma_f32 v9, -v5, v7, 1.0
	v_fmac_f32_e32 v7, v9, v7
	v_mul_f32_e32 v9, v8, v7
	v_fma_f32 v10, -v5, v9, v8
	v_fmac_f32_e32 v9, v10, v7
	v_fma_f32 v5, -v5, v9, v8
	v_div_fmas_f32 v5, v5, v7, v9
	v_div_fixup_f32 v2, v5, v3, v2
	ds_write_b32 v14, v2 offset:16640
	s_waitcnt vmcnt(1)
	v_mov_b32_e32 v2, v30
	v_mul_f32_e32 v3, 0xbfb8aa3b, v2
	v_exp_f32_e32 v3, v3
	s_nop 0
	v_add_f32_e32 v3, 1.0, v3
	v_div_scale_f32 v5, s[6:7], v3, v3, v2
	v_rcp_f32_e32 v7, v5
	v_div_scale_f32 v8, vcc, v2, v3, v2
	v_fma_f32 v9, -v5, v7, 1.0
	v_fmac_f32_e32 v7, v9, v7
	v_mul_f32_e32 v9, v8, v7
	v_fma_f32 v10, -v5, v9, v8
	v_fmac_f32_e32 v9, v10, v7
	v_fma_f32 v5, -v5, v9, v8
	v_div_fmas_f32 v5, v5, v7, v9
	v_div_fixup_f32 v2, v5, v3, v2
	ds_write_b32 v14, v2 offset:16896
	s_waitcnt vmcnt(0)
	v_mov_b32_e32 v2, v31
	v_mul_f32_e32 v3, 0xbfb8aa3b, v2
	v_exp_f32_e32 v3, v3
	s_nop 0
	v_add_f32_e32 v3, 1.0, v3
	v_div_scale_f32 v5, s[6:7], v3, v3, v2
	v_rcp_f32_e32 v7, v5
	v_div_scale_f32 v8, vcc, v2, v3, v2
	v_fma_f32 v9, -v5, v7, 1.0
	v_fmac_f32_e32 v7, v9, v7
	v_mul_f32_e32 v9, v8, v7
	v_fma_f32 v10, -v5, v9, v8
	v_fmac_f32_e32 v9, v10, v7
	v_fma_f32 v5, -v5, v9, v8
	v_div_fmas_f32 v5, v5, v7, v9
	v_div_fixup_f32 v2, v5, v3, v2
	ds_write_b32 v14, v2 offset:17152
.LBB0_19:
	s_or_b64 exec, exec, s[0:1]
	s_mov_b32 s89, s24
	s_movk_i32 s4, 0xff
	s_cmp_lg_u32 s98, 0
	s_cbranch_scc1 .Lada_lim
	s_cmp_eq_u32 s3, 0x100
	s_cselect_b32 s4, 63, s4
.Lada_lim:
	s_waitcnt lgkmcnt(0)
	s_barrier
	s_cmp_gt_i32 s60, s4
	s_cbranch_scc1 .LBB0_47
	s_add_u32 s6, s86, 0x10000
	s_addc_u32 s7, s87, 0
	s_lshl_b32 s4, s44, 10
	s_add_i32 s61, s4, 0
	s_mul_i32 s4, s44, 0x500
	v_readlane_b32 s12, v252, 8
	s_lshl_b32 s8, s44, 8
	s_add_i32 s4, s61, s4
	s_mul_i32 s9, s44, 0xc00000
	v_readlane_b32 s20, v252, 16
	v_lshlrev_b32_e32 v2, 2, v78
	s_mul_hi_i32 s10, s8, 0xc000
	v_readlane_b32 s21, v252, 17
	s_add_u32 s8, s20, s9
	v_ashrrev_i32_e32 v3, 31, v2
	v_lshl_add_u32 v79, v78, 4, s4
	s_movk_i32 s4, 0x240
	s_addc_u32 s9, s21, s10
	v_cmp_gt_i32_e64 s[0:1], 48, v78
	v_cmp_gt_i32_e64 s[4:5], s4, v1
	v_lshl_add_u64 v[56:57], v[2:3], 2, s[8:9]
	s_mov_b32 s62, s60
	s_mov_b32 s63, s60
	v_readlane_b32 s13, v252, 9
	v_readlane_b32 s14, v252, 10
	v_readlane_b32 s15, v252, 11
	v_readlane_b32 s16, v252, 12
	v_readlane_b32 s17, v252, 13
	v_readlane_b32 s18, v252, 14
	v_readlane_b32 s19, v252, 15
	v_readlane_b32 s22, v252, 18
	v_readlane_b32 s23, v252, 19
	v_readlane_b32 s24, v252, 20
	v_readlane_b32 s25, v252, 21
	v_readlane_b32 s26, v252, 22
	v_readlane_b32 s27, v252, 23
	s_branch .LBB0_22

; #define GAS __attribute__((address_space(1)))
; DI unsigned f2bf(float f) { unsigned u = __builtin_bit_cast(unsigned, f); return (u + 0x7fffu + ((u >> 16) & 1u)) >> 16; }
; DI void phase_prologue(const Frame& F0, const Args& a) {
;     ...
;         const int gt = F.vcu * 512 + F.tid, NT = F.G * 512;
;         bf16* dftc = (bf16*)(ws + WS_DFTC); bf16* m1 = (bf16*)(ws + WS_M1); bf16* m2 = (bf16*)(ws + WS_M2); bf16* mc = (bf16*)(ws + WS_MC);
;         for (int i = gt; i < 512 * 512; i += NT) { const int n = i >> 9, cidx = i & 511, part = n >> 8, m = n & 255; float s, c; sincospif(2.0f * (float)((cidx * m) & 511) / 512.0f, &s, &c);
;             *(GAS bf16*)(dftc + i) = (bf16)f2bf(part == 0 ? c : (m == 0 ? ((cidx & 1) ? -1.0f : 1.0f) : -s)); }
.LBB0_47:
	s_cmp_lg_u32 s98, 0
	s_cbranch_scc1 .Lada_hook_ret
	v_lshl_add_u32 v10, s60, 9, v1
	v_cmp_gt_i32_e32 vcc, s75, v10
	v_add_u32_e32 v11, s71, v10
	s_and_saveexec_b64 s[90:91], vcc
	s_mov_b32 s24, s89
	s_mov_b32 s12, 0x3b000000
	s_mov_b32 s14, 0xbf1f24be
	s_mov_b32 s16, 0x3e642e9d
	s_cbranch_execz .LBB0_55
	v_and_b32_e32 v1, 1, v1
	v_cmp_eq_u32_e32 vcc, 0, v1
	v_max_i32_e32 v1, 0x40000, v11
	s_add_u32 s92, s86, 0x15aa0000
	v_cndmask_b32_e64 v2, -1.0, 1.0, vcc
	v_cmp_gt_i32_e32 vcc, s75, v11
	s_addc_u32 s93, s87, 0
	s_mov_b64 s[0:1], -1
	v_cndmask_b32_e64 v3, 1, 2, vcc
	v_subb_co_u32_e32 v1, vcc, v1, v11, vcc
	v_mul_hi_u32 v4, v1, v72
	v_mul_lo_u32 v5, v4, s71
	v_sub_u32_e32 v1, v1, v5
	v_add_u32_e32 v5, 1, v4
	v_cmp_le_u32_e32 vcc, s71, v1
	s_nop 1
	v_cndmask_b32_e32 v4, v4, v5, vcc
	v_subrev_u32_e32 v5, s71, v1
	v_cndmask_b32_e32 v1, v1, v5, vcc
	v_add_u32_e32 v5, 1, v4
	v_cmp_le_u32_e32 vcc, s71, v1
	s_nop 1
	v_cndmask_b32_e32 v1, v4, v5, vcc
	v_add_u32_e32 v9, v3, v1
	v_cmp_lt_u32_e32 vcc, 3, v9
	v_mov_b32_e32 v4, v10
	s_and_saveexec_b64 s[94:95], vcc
	s_cbranch_execz .LBB0_52
	v_and_b32_e32 v38, -4, v9
	s_mul_i32 s0, s3, 0x600
	v_mov_b32_e32 v1, v2
	v_mov_b32_e32 v4, v2
	v_mov_b32_e32 v3, v2
	v_add_u32_e32 v5, s0, v10
	v_add_u32_e32 v6, s77, v10
	v_add_u32_e32 v7, s71, v10
	v_add_u32_e32 v8, 0, v10
	s_mov_b64 s[96:97], 0
	v_mov_b32_e32 v39, v38

; DI void phase_prologue(const Frame& F0, const Args& a) {
;     ...
;         for (int unit = F.vcu; unit < DEPTH * 64; unit += F.G) {
;             const int li = unit >> 6, cb = unit & 63, n0 = cb * 192;
;             const float* W = a.ada_w + (size_t)li * DM * NADA + n0;
; DI void phase_scan(const Frame& F0, const Args& a, int colmajor) {
;     ...
;     for (int it = F.vcu; it < 256; it += F.G) {
;         if ((it & 31) >= 16) continue;
.Lconv_scan_idle:
	s_cmp_eq_u32 s3, 0x100
	s_cbranch_scc0 .LBB0_821
	v_writelane_b32 v240, s11, 0
	v_writelane_b32 v240, s20, 1
	v_writelane_b32 v240, s21, 2
	v_writelane_b32 v240, s22, 3
	v_writelane_b32 v240, s26, 4
	v_writelane_b32 v240, s28, 5
	v_writelane_b32 v240, s29, 6
	v_writelane_b32 v240, s30, 7
	v_writelane_b32 v240, s31, 8
	v_writelane_b32 v240, s43, 9
	v_writelane_b32 v240, s44, 10
	v_writelane_b32 v240, s50, 11
	v_writelane_b32 v240, s80, 12
	v_writelane_b32 v240, s86, 13
	v_writelane_b32 v240, s87, 14
	v_writelane_b32 v240, s89, 15
	v_writelane_b32 v240, s96, 16
	v_writelane_b32 v240, s97, 17
	v_mov_b32_e32 v241, v1
	v_mov_b32_e32 v242, v3
	v_mov_b32_e32 v243, v55
	v_mov_b32_e32 v244, v73
	v_readlane_b32 s0, v255, 17
	v_readlane_b32 s1, v252, 48
	s_lshr_b32 s4, s1, 5
	s_lshl_b32 s4, s4, 4
	s_and_b32 s5, s1, 15
	s_or_b32 s4, s4, s5
	s_cmp_eq_u32 s0, 0
	s_cbranch_scc1 .Lah_l0
	s_cmp_ge_u32 s4, 64
	s_cbranch_scc1 .Lada_hook_ret
	s_addk_i32 s4, 0x80
.Lah_l0:
	s_add_i32 s99, s4, 64
	s_mov_b32 s98, 1
	s_mov_b32 s43, 0xc000
	s_movk_i32 s79, 0x6000
	v_readlane_b32 s50, v252, 49
	v_mov_b32_e32 v55, 0
	v_mov_b32_e32 v73, 0xff
	s_branch .LBB0_12
.Lada_hook_ret:
	s_mov_b32 s98, 0
	v_readlane_b32 s0, v255, 17
	v_readlane_b32 s1, v252, 48
	v_readlane_b32 s44, v252, 49
	v_readlane_b32 s86, v252, 46
	v_readlane_b32 s87, v252, 47
	v_mov_b32_e32 v78, v222
	s_lshr_b32 s4, s1, 5
	s_lshl_b32 s4, s4, 4
	s_and_b32 s5, s1, 15
	s_or_b32 s4, s4, s5
	s_cmp_ge_u32 s44, 8
	s_cbranch_scc1 .Lconv_ret_scan
	s_mul_i32 s4, s4, 8
	s_add_i32 s90, s4, s44
	s_movk_i32 s93, 0x400
	s_mov_b32 s4, 0xac20
	s_mov_b32 s5, 0x9400
	s_cmp_eq_u32 s0, 0
	s_cselect_b32 s92, 2, 3
	s_cselect_b32 s91, s4, s5
	s_cmp_lt_i32 s90, s91
	s_cbranch_scc1 .Lconv_entry
.Lconv_ret_scan:
	s_waitcnt vmcnt(0) lgkmcnt(0)
	v_readlane_b32 s11, v240, 0
	v_readlane_b32 s20, v240, 1
	v_readlane_b32 s21, v240, 2
	v_readlane_b32 s22, v240, 3
	v_readlane_b32 s26, v240, 4
	v_readlane_b32 s28, v240, 5
	v_readlane_b32 s29, v240, 6
	v_readlane_b32 s30, v240, 7
	v_readlane_b32 s31, v240, 8
	v_readlane_b32 s43, v240, 9
	v_readlane_b32 s44, v240, 10
	v_readlane_b32 s50, v240, 11
	v_readlane_b32 s80, v240, 12
	v_readlane_b32 s86, v240, 13
	v_readlane_b32 s87, v240, 14
	v_readlane_b32 s89, v240, 15
	v_readlane_b32 s96, v240, 16
	v_readlane_b32 s97, v240, 17
	v_mov_b32_e32 v1, v241
	v_mov_b32_e32 v3, v242
	v_mov_b32_e32 v55, v243
	v_mov_b32_e32 v73, v244
	s_nop 4
	s_branch .LBB0_821
